# P2 gates loop: waves 4-7 start each unit s_sleep 9 late (stagger SIMD partners)
# speedup vs baseline: 1.0002x; 1.0002x over previous
.LBB0_403:
	s_cmp_lt_u32 s45, 4
	s_cbranch_scc1 .Lstag_p2
	s_sleep 9
